# sample_proj (G2 and G4): the residual-base and gate loads of the final combine are issued at the top of the column-group loop under the tid<64 mask instead of after the partial-sum reduction; on top o
# baseline (speedup 1.0000x reference)
.LBB0_1474:
	s_ashr_i32 s5, s4, 31
	s_mov_b64 s[6:7], exec
	s_and_b64 exec, exec, vcc
	v_lshl_add_u64 v[122:123], v[10:11], 0, s[4:5]
	v_lshlrev_b64 v[122:123], 2, v[122:123]
	v_lshl_add_u64 v[124:125], s[72:73], 0, v[122:123]
	global_load_dword v120, v[124:125], off
	v_lshl_add_u64 v[124:125], s[4:5], 2, v[12:13]
	global_load_dword v121, v[124:125], off
	s_mov_b64 exec, s[6:7]
	global_load_dwordx4 v[2:5], v[6:7], off
	v_add_u32_e32 v18, s4, v14
	v_ashrrev_i32_e32 v19, 31, v18
	v_lshlrev_b64 v[18:19], 12, v[18:19]
	v_lshl_add_u64 v[46:47], v[8:9], 0, v[18:19]
	global_load_dwordx4 v[18:21], v[6:7], off offset:64
	global_load_dwordx4 v[22:25], v[46:47], off
	global_load_dwordx4 v[26:29], v[46:47], off offset:64
	global_load_dwordx4 v[30:33], v[6:7], off offset:128
	global_load_dwordx4 v[34:37], v[6:7], off offset:192
	global_load_dwordx4 v[38:41], v[46:47], off offset:128
	global_load_dwordx4 v[42:45], v[6:7], off offset:256
	s_waitcnt vmcnt(5)
	v_mfma_f32_16x16x32_bf16 v[2:5], v[2:5], v[22:25], 0
	global_load_dwordx4 v[22:25], v[46:47], off offset:192
	s_waitcnt vmcnt(5)
	v_mfma_f32_16x16x32_bf16 v[2:5], v[18:21], v[26:29], v[2:5]
	global_load_dwordx4 v[18:21], v[46:47], off offset:256
	s_waitcnt vmcnt(3)
	v_mfma_f32_16x16x32_bf16 v[2:5], v[30:33], v[38:41], v[2:5]
	global_load_dwordx4 v[26:29], v[6:7], off offset:320
	global_load_dwordx4 v[30:33], v[6:7], off offset:384
	s_waitcnt vmcnt(3)
	v_mfma_f32_16x16x32_bf16 v[2:5], v[34:37], v[22:25], v[2:5]
	global_load_dwordx4 v[22:25], v[46:47], off offset:320
	s_waitcnt vmcnt(3)
	v_mfma_f32_16x16x32_bf16 v[2:5], v[42:45], v[18:21], v[2:5]
	global_load_dwordx4 v[18:21], v[46:47], off offset:384
	s_waitcnt vmcnt(1)
	v_mfma_f32_16x16x32_bf16 v[2:5], v[26:29], v[22:25], v[2:5]
	global_load_dwordx4 v[22:25], v[6:7], off offset:448
	s_waitcnt vmcnt(1)
	v_mfma_f32_16x16x32_bf16 v[2:5], v[30:33], v[18:21], v[2:5]
	global_load_dwordx4 v[18:21], v[46:47], off offset:448
	s_barrier
	s_waitcnt vmcnt(0)
	v_mfma_f32_16x16x32_bf16 v[2:5], v[22:25], v[18:21], v[2:5]
	s_and_saveexec_b64 s[6:7], s[0:1]
	s_cbranch_execz .LBB0_1476
	s_nop 5
	ds_write2_b32 v16, v2, v3 offset1:8
	ds_write2_b32 v16, v4, v5 offset0:16 offset1:24
.LBB0_1476:
	s_or_b64 exec, exec, s[6:7]
	s_waitcnt lgkmcnt(0)
	s_barrier
	s_and_saveexec_b64 s[6:7], vcc
	s_cbranch_execz .LBB0_1473
	s_nop 0
	ds_read2st64_b32 v[2:3], v15 offset1:1
	s_ashr_i32 s5, s4, 31
	s_waitcnt lgkmcnt(0)
	v_add_f32_e32 v2, 0, v2
	v_add_f32_e32 v4, v2, v3
	ds_read2st64_b32 v[2:3], v15 offset0:2 offset1:3
	s_waitcnt lgkmcnt(0)
	v_add_f32_e32 v2, v4, v2
	v_add_f32_e32 v4, v2, v3
	ds_read2st64_b32 v[2:3], v15 offset0:4 offset1:5
	s_waitcnt lgkmcnt(0)
	v_add_f32_e32 v2, v4, v2
	v_add_f32_e32 v4, v2, v3
	ds_read2st64_b32 v[2:3], v15 offset0:6 offset1:7
	s_waitcnt lgkmcnt(0)
	v_add_f32_e32 v2, v4, v2
	v_add_f32_e32 v17, v2, v3
	v_lshl_add_u64 v[2:3], v[10:11], 0, s[4:5]
	v_lshlrev_b64 v[2:3], 2, v[2:3]
	v_lshl_add_u64 v[4:5], s[72:73], 0, v[2:3]
	v_mov_b32_e32 v18, v120
	v_lshl_add_u64 v[4:5], s[4:5], 2, v[12:13]
	v_mov_b32_e32 v4, v121
	v_lshl_add_u64 v[2:3], s[80:81], 0, v[2:3]
	s_waitcnt vmcnt(0)
	v_fmac_f32_e32 v18, v17, v4
	global_store_dword v[2:3], v18, off
	s_branch .LBB0_1473

.LBB0_1743:
	s_ashr_i32 s9, s8, 31
	s_mov_b64 s[10:11], exec
	s_and_b64 exec, exec, vcc
	v_lshl_add_u64 v[122:123], v[10:11], 0, s[8:9]
	v_lshlrev_b64 v[122:123], 2, v[122:123]
	v_lshl_add_u64 v[124:125], s[80:81], 0, v[122:123]
	global_load_dword v120, v[124:125], off
	v_lshl_add_u64 v[124:125], s[8:9], 2, v[12:13]
	global_load_dword v121, v[124:125], off
	s_mov_b64 exec, s[10:11]
	global_load_dwordx4 v[18:21], v[6:7], off
	v_add_u32_e32 v2, s8, v14
	s_movk_i32 s9, 0x2c00
	v_mad_i64_i32 v[2:3], s[10:11], v2, s9, v[8:9]
	global_load_dwordx4 v[22:25], v[2:3], off
	global_load_dwordx4 v[26:29], v[6:7], off offset:64
	global_load_dwordx4 v[30:33], v[6:7], off offset:128
	global_load_dwordx4 v[34:37], v[2:3], off offset:64
	global_load_dwordx4 v[38:41], v[6:7], off offset:192
	global_load_dwordx4 v[42:45], v[2:3], off offset:128
	global_load_dwordx4 v[46:49], v[6:7], off offset:256
	global_load_dwordx4 v[50:53], v[2:3], off offset:192
	global_load_dwordx4 v[54:57], v[6:7], off offset:320
	global_load_dwordx4 v[58:61], v[2:3], off offset:256
	global_load_dwordx4 v[62:65], v[6:7], off offset:384
	global_load_dwordx4 v[68:71], v[2:3], off offset:320
	s_waitcnt vmcnt(11)
	v_mfma_f32_16x16x32_bf16 v[18:21], v[18:21], v[22:25], 0
	global_load_dwordx4 v[22:25], v[2:3], off offset:384
	s_waitcnt vmcnt(9)
	v_mfma_f32_16x16x32_bf16 v[18:21], v[26:29], v[34:37], v[18:21]
	global_load_dwordx4 v[26:29], v[6:7], off offset:448
	global_load_dwordx4 v[34:37], v[6:7], off offset:512
	s_waitcnt vmcnt(9)
	v_mfma_f32_16x16x32_bf16 v[18:21], v[30:33], v[42:45], v[18:21]
	global_load_dwordx4 v[30:33], v[2:3], off offset:448
	global_load_dwordx4 v[42:45], v[6:7], off offset:576
	s_waitcnt vmcnt(9)
	v_mfma_f32_16x16x32_bf16 v[18:21], v[38:41], v[50:53], v[18:21]
	global_load_dwordx4 v[38:41], v[2:3], off offset:512
	global_load_dwordx4 v[50:53], v[6:7], off offset:640
	s_waitcnt vmcnt(9)
	v_mfma_f32_16x16x32_bf16 v[18:21], v[46:49], v[58:61], v[18:21]
	global_load_dwordx4 v[46:49], v[2:3], off offset:576
	global_load_dwordx4 v[58:61], v[6:7], off offset:704
	s_waitcnt vmcnt(9)
	v_mfma_f32_16x16x32_bf16 v[18:21], v[54:57], v[68:71], v[18:21]
	global_load_dwordx4 v[54:57], v[2:3], off offset:640
	s_waitcnt vmcnt(9)
	v_mfma_f32_16x16x32_bf16 v[18:21], v[62:65], v[22:25], v[18:21]
	global_load_dwordx4 v[22:25], v[2:3], off offset:704
	s_waitcnt vmcnt(7)
	v_mfma_f32_16x16x32_bf16 v[18:21], v[26:29], v[30:33], v[18:21]
	global_load_dwordx4 v[26:29], v[6:7], off offset:768
	global_load_dwordx4 v[30:33], v[6:7], off offset:832
	s_waitcnt vmcnt(7)
	v_mfma_f32_16x16x32_bf16 v[18:21], v[34:37], v[38:41], v[18:21]
	global_load_dwordx4 v[34:37], v[2:3], off offset:768
	global_load_dwordx4 v[38:41], v[6:7], off offset:896
	s_waitcnt vmcnt(7)
	v_mfma_f32_16x16x32_bf16 v[18:21], v[42:45], v[46:49], v[18:21]
	global_load_dwordx4 v[42:45], v[2:3], off offset:832
	global_load_dwordx4 v[46:49], v[6:7], off offset:960
	s_waitcnt vmcnt(7)
	v_mfma_f32_16x16x32_bf16 v[18:21], v[50:53], v[54:57], v[18:21]
	global_load_dwordx4 v[50:53], v[2:3], off offset:896
	s_waitcnt vmcnt(7)
	v_mfma_f32_16x16x32_bf16 v[18:21], v[58:61], v[22:25], v[18:21]
	global_load_dwordx4 v[22:25], v[2:3], off offset:960
	s_waitcnt vmcnt(5)
	v_mfma_f32_16x16x32_bf16 v[18:21], v[26:29], v[34:37], v[18:21]
	global_load_dwordx4 v[26:29], v[6:7], off offset:1024
	global_load_dwordx4 v[34:37], v[6:7], off offset:1088
	s_waitcnt vmcnt(5)
	v_mfma_f32_16x16x32_bf16 v[18:21], v[30:33], v[42:45], v[18:21]
	global_load_dwordx4 v[30:33], v[2:3], off offset:1024
	global_load_dwordx4 v[42:45], v[6:7], off offset:1152
	s_waitcnt vmcnt(5)
	v_mfma_f32_16x16x32_bf16 v[18:21], v[38:41], v[50:53], v[18:21]
	global_load_dwordx4 v[38:41], v[2:3], off offset:1088
	s_waitcnt vmcnt(5)
	v_mfma_f32_16x16x32_bf16 v[18:21], v[46:49], v[22:25], v[18:21]
	global_load_dwordx4 v[22:25], v[2:3], off offset:1152
	s_waitcnt vmcnt(3)
	v_mfma_f32_16x16x32_bf16 v[18:21], v[26:29], v[30:33], v[18:21]
	global_load_dwordx4 v[26:29], v[6:7], off offset:1216
	global_load_dwordx4 v[30:33], v[6:7], off offset:1280
	s_waitcnt vmcnt(3)
	v_mfma_f32_16x16x32_bf16 v[18:21], v[34:37], v[38:41], v[18:21]
	global_load_dwordx4 v[34:37], v[2:3], off offset:1216
	s_waitcnt vmcnt(3)
	v_mfma_f32_16x16x32_bf16 v[18:21], v[42:45], v[22:25], v[18:21]
	global_load_dwordx4 v[22:25], v[2:3], off offset:1280
	s_nop 0
	global_load_dwordx4 v[2:5], v[2:3], off offset:1344
	s_waitcnt vmcnt(2)
	v_mfma_f32_16x16x32_bf16 v[18:21], v[26:29], v[34:37], v[18:21]
	global_load_dwordx4 v[26:29], v[6:7], off offset:1344
	s_barrier
	s_waitcnt vmcnt(2)
	v_mfma_f32_16x16x32_bf16 v[18:21], v[30:33], v[22:25], v[18:21]
	s_waitcnt vmcnt(0)
	v_mfma_f32_16x16x32_bf16 v[2:5], v[26:29], v[2:5], v[18:21]
	s_and_saveexec_b64 s[10:11], s[0:1]
	s_cbranch_execz .LBB0_1745
	s_nop 5
	ds_write2_b32 v16, v2, v3 offset1:8
	ds_write2_b32 v16, v4, v5 offset0:16 offset1:24
.LBB0_1745:
	s_or_b64 exec, exec, s[10:11]
	s_waitcnt lgkmcnt(0)
	s_barrier
	s_and_saveexec_b64 s[10:11], vcc
	s_cbranch_execz .LBB0_1742
	s_nop 0
	ds_read2st64_b32 v[2:3], v15 offset1:1
	s_ashr_i32 s9, s8, 31
	s_waitcnt lgkmcnt(0)
	v_add_f32_e32 v2, 0, v2
	v_add_f32_e32 v4, v2, v3
	ds_read2st64_b32 v[2:3], v15 offset0:2 offset1:3
	s_waitcnt lgkmcnt(0)
	v_add_f32_e32 v2, v4, v2
	v_add_f32_e32 v4, v2, v3
	ds_read2st64_b32 v[2:3], v15 offset0:4 offset1:5
	s_waitcnt lgkmcnt(0)
	v_add_f32_e32 v2, v4, v2
	v_add_f32_e32 v4, v2, v3
	ds_read2st64_b32 v[2:3], v15 offset0:6 offset1:7
	s_waitcnt lgkmcnt(0)
	v_add_f32_e32 v2, v4, v2
	v_add_f32_e32 v17, v2, v3
	v_lshl_add_u64 v[2:3], v[10:11], 0, s[8:9]
	v_lshlrev_b64 v[2:3], 2, v[2:3]
	v_lshl_add_u64 v[4:5], s[80:81], 0, v[2:3]
	v_mov_b32_e32 v18, v120
	v_lshl_add_u64 v[4:5], s[8:9], 2, v[12:13]
	v_mov_b32_e32 v4, v121
	v_lshl_add_u64 v[2:3], s[4:5], 0, v[2:3]
	s_waitcnt vmcnt(0)
	v_fmac_f32_e32 v18, v17, v4
	global_store_dword v[2:3], v18, off
	s_branch .LBB0_1742
